# GU main loops: rebalanced LDS-DMA stage loads from 2/6/2/6 to 4/4/4/4 per phase (SA(0,0) moved P2->P3, SA(1,0) moved P4->next P1), waits 8/6/8/6
# baseline (speedup 1.0000x reference)
; #define LAS __attribute__((address_space(3)))
; #define PG8_STAGE(bufoff, gbase, voff) do { _Pragma("unroll") for (int _i = 0; _i < 2; ++_i) \
;         __builtin_amdgcn_global_load_lds((const unsigned*)((const char*)(gbase) + (voff)[_i]), (LAS unsigned*)(lds + (bufoff) + ldsw + _i * 8192), 16, 0, 0); } while (0)
; #define PG8_LDA(dst, b, h) do { _Pragma("unroll") for (int m = 0; m < 4; ++m) _Pragma("unroll") for (int k = 0; k < 2; ++k) dst[m][k] = *(const LAS bf16x8*)(lds + PG8_SA(b, h) + aoff + m * 2048 + k * 1024); } while (0)
; #define PG8_LDB(dst, b, h) do { _Pragma("unroll") for (int n = 0; n < 2; ++n) _Pragma("unroll") for (int k = 0; k < 2; ++k) dst[n][k] = *(const LAS bf16x8*)(lds + PG8_SB(b, h) + boff + n * 2048 + k * 1024); } while (0)
; #define PG8_WAIT_V(n) asm volatile("s_waitcnt vmcnt(" #n ")" ::: "memory")
; #define PG8_WAIT_L(n) asm volatile("s_waitcnt lgkmcnt(" #n ")" ::: "memory")
; template <class Epi>
; __device__ __forceinline__ void gemm_phase(LAS unsigned char* lds, const int tid, const Gemm g, const StaticOrder& S, const Epi& E) {
;     ...
;         for (int t = 0; t < nt; t += 2) {
;             const bool last = (t == nt - 2);
;             const char* a1 = cA + (size_t)(t + 1) * kstep;
;             const char* a2 = last ? nA : cA + (size_t)(t + 2) * kstep; const char* b2 = last ? nB : cB + (size_t)(t + 2) * kstep;
;             const char* a3 = a2 + kstep; const char* b3 = b2 + kstep;
;             if constexpr (Epi::SS_LDS) { if (last) {
;                 const char* sp = (const char*)E.ss + (size_t)cur.pm * (256 * 64) + (size_t)tid * 16;
;                 __builtin_amdgcn_global_load_lds((const unsigned*)sp, (LAS unsigned*)(lds + RS_OFF + ldsw), 16, 0, 0);
;                 __builtin_amdgcn_global_load_lds((const unsigned*)(sp + 8192), (LAS unsigned*)(lds + RS_OFF + 8192 + ldsw), 16, 0, 0); } }
;     ...
;             PG8_LDB(B0, 0, 0); PG8_LDB(B1, 0, 1); PG8_SCHED; PG8_LDA(At, 0, 0); PG8_STAGE(PG8_SA(1, 1), a1 + hstepA, voffA);
;             PG8_WAIT_V(8); PG8_WAIT_L(0); PG8_BAR; PG8_MMA(0, 0, At, B0); PG8_MMA(0, 1, At, B1); PG8_BAR; PG8_SCHED;
;             PG8_LDA(At, 0, 1); PG8_STAGE(PG8_SB(0, 0), b2, voffB); PG8_STAGE(PG8_SB(0, 1), b2 + hstepB, voffB); PG8_STAGE(PG8_SA(0, 0), a2, voffA);
;             PG8_WAIT_V(8); PG8_WAIT_L(0); PG8_BAR; PG8_MMA(1, 0, At, B0); PG8_MMA(1, 1, At, B1); PG8_BAR; PG8_SCHED;
.LBB0_263:
	v_add_u32_e32 v168, s51, v151
	v_add_u32_e32 v184, s52, v151
	ds_read_b128 v[156:159], v168
	ds_read_b128 v[160:163], v168 offset:1024
	ds_read_b128 v[164:167], v168 offset:2048
	ds_read_b128 v[168:171], v168 offset:3072
	ds_read_b128 v[172:175], v184
	ds_read_b128 v[176:179], v184 offset:1024
	ds_read_b128 v[180:183], v184 offset:2048
	ds_read_b128 v[184:187], v184 offset:3072
	s_add_i32 s58, s58, 2
	s_add_u32 s30, s26, 0xfffc0080
	s_addc_u32 s31, s27, -1
	s_and_b64 s[28:29], s[28:29], exec
	s_cselect_b32 s31, s17, s31
	s_cselect_b32 s30, s19, s30
	s_cselect_b32 s29, s55, s57
	s_cselect_b32 s28, s56, s25
	s_add_u32 s60, s26, 0xfffc0000
	s_addc_u32 s61, s27, -1
	v_lshl_add_u64 v[222:223], s[60:61], 0, v[140:141]
	s_mov_b32 m0, s47
	v_lshl_add_u64 v[224:225], s[60:61], 0, v[138:139]
	global_load_lds_dwordx4 v[222:223], off
	s_mov_b32 m0, s48
	s_nop 0
	global_load_lds_dwordx4 v[224:225], off
	v_lshl_add_u64 v[220:221], s[26:27], 0, v[140:141]
	s_add_i32 m0, s41, 0xc000
	ds_read_b128 v[188:191], v153
	ds_read_b128 v[192:195], v153 offset:1024
	ds_read_b128 v[196:199], v153 offset:2048
	ds_read_b128 v[200:203], v153 offset:3072
	ds_read_b128 v[204:207], v153 offset:4096
	ds_read_b128 v[208:211], v153 offset:5120
	ds_read_b128 v[212:215], v153 offset:6144
	ds_read_b128 v[216:219], v153 offset:7168
	global_load_lds_dwordx4 v[220:221], off
	v_lshl_add_u64 v[220:221], s[26:27], 0, v[138:139]
	s_add_i32 m0, s41, 0xe000
	s_nop 0
	global_load_lds_dwordx4 v[220:221], off
	s_waitcnt vmcnt(8)
	s_waitcnt lgkmcnt(0)
	s_barrier
	s_setprio 1
	v_mfma_f32_16x16x32_bf16 v[120:123], v[156:159], v[188:191], v[120:123]
	v_mfma_f32_16x16x32_bf16 v[116:119], v[164:167], v[188:191], v[116:119]
	v_mfma_f32_16x16x32_bf16 v[108:111], v[156:159], v[196:199], v[108:111]
	v_mfma_f32_16x16x32_bf16 v[100:103], v[164:167], v[196:199], v[100:103]
	v_mfma_f32_16x16x32_bf16 v[92:95], v[156:159], v[204:207], v[92:95]
	v_mfma_f32_16x16x32_bf16 v[84:87], v[164:167], v[204:207], v[84:87]
	v_mfma_f32_16x16x32_bf16 v[76:79], v[156:159], v[212:215], v[76:79]
	v_mfma_f32_16x16x32_bf16 v[68:71], v[164:167], v[212:215], v[68:71]
	v_mfma_f32_16x16x32_bf16 v[120:123], v[160:163], v[192:195], v[120:123]
	v_mfma_f32_16x16x32_bf16 v[116:119], v[168:171], v[192:195], v[116:119]
	v_mfma_f32_16x16x32_bf16 v[108:111], v[160:163], v[200:203], v[108:111]
	v_mfma_f32_16x16x32_bf16 v[100:103], v[168:171], v[200:203], v[100:103]
	v_mfma_f32_16x16x32_bf16 v[92:95], v[160:163], v[208:211], v[92:95]
	v_mfma_f32_16x16x32_bf16 v[84:87], v[168:171], v[208:211], v[84:87]
	v_mfma_f32_16x16x32_bf16 v[76:79], v[160:163], v[216:219], v[76:79]
	v_mfma_f32_16x16x32_bf16 v[68:71], v[168:171], v[216:219], v[68:71]
	v_mfma_f32_16x16x32_bf16 v[124:127], v[172:175], v[188:191], v[124:127]
	v_mfma_f32_16x16x32_bf16 v[112:115], v[180:183], v[188:191], v[112:115]
	v_mfma_f32_16x16x32_bf16 v[104:107], v[172:175], v[196:199], v[104:107]
	v_mfma_f32_16x16x32_bf16 v[96:99], v[180:183], v[196:199], v[96:99]
	v_mfma_f32_16x16x32_bf16 v[88:91], v[172:175], v[204:207], v[88:91]
	v_mfma_f32_16x16x32_bf16 v[80:83], v[180:183], v[204:207], v[80:83]
	v_mfma_f32_16x16x32_bf16 v[72:75], v[172:175], v[212:215], v[72:75]
	v_mfma_f32_16x16x32_bf16 v[64:67], v[180:183], v[212:215], v[64:67]
	v_mfma_f32_16x16x32_bf16 v[124:127], v[176:179], v[192:195], v[124:127]
	v_mfma_f32_16x16x32_bf16 v[112:115], v[184:187], v[192:195], v[112:115]
	v_mfma_f32_16x16x32_bf16 v[104:107], v[176:179], v[200:203], v[104:107]
	v_mfma_f32_16x16x32_bf16 v[96:99], v[184:187], v[200:203], v[96:99]
	v_mfma_f32_16x16x32_bf16 v[88:91], v[176:179], v[208:211], v[88:91]
	v_mfma_f32_16x16x32_bf16 v[80:83], v[184:187], v[208:211], v[80:83]
	v_mfma_f32_16x16x32_bf16 v[72:75], v[176:179], v[216:219], v[72:75]
	v_mfma_f32_16x16x32_bf16 v[64:67], v[184:187], v[216:219], v[64:67]
	s_setprio 0
	s_barrier
	s_add_i32 s59, s51, s38
	v_lshl_add_u64 v[220:221], s[28:29], 0, v[132:133]
	s_mov_b32 m0, s59
	ds_read_b128 v[188:191], v153 offset:16384
	ds_read_b128 v[192:195], v153 offset:17408
	ds_read_b128 v[196:199], v153 offset:18432
	ds_read_b128 v[200:203], v153 offset:19456
	ds_read_b128 v[204:207], v153 offset:20480
	ds_read_b128 v[208:211], v153 offset:21504
	ds_read_b128 v[212:215], v153 offset:22528
	ds_read_b128 v[216:219], v153 offset:23552
	global_load_lds_dwordx4 v[220:221], off
	s_add_i32 m0, s59, 0x2000
	s_add_u32 s60, s28, 0x40000
	v_lshl_add_u64 v[222:223], s[28:29], 0, v[128:129]
	s_addc_u32 s61, s29, 0
	s_add_i32 s59, s52, s38
	global_load_lds_dwordx4 v[222:223], off
	v_lshl_add_u64 v[224:225], s[60:61], 0, v[132:133]
	s_mov_b32 m0, s59
	s_nop 0
	global_load_lds_dwordx4 v[224:225], off
	v_lshl_add_u64 v[224:225], s[60:61], 0, v[128:129]
	s_add_i32 m0, s59, 0x2000
	s_nop 0
	global_load_lds_dwordx4 v[224:225], off
	s_waitcnt vmcnt(6)
	s_waitcnt lgkmcnt(0)
	s_barrier
; #define PG8_STAGE(bufoff, gbase, voff) do { _Pragma("unroll") for (int _i = 0; _i < 2; ++_i) \
;         __builtin_amdgcn_global_load_lds((const unsigned*)((const char*)(gbase) + (voff)[_i]), (LAS unsigned*)(lds + (bufoff) + ldsw + _i * 8192), 16, 0, 0); } while (0)
; #define PG8_LDA(dst, b, h) do { _Pragma("unroll") for (int m = 0; m < 4; ++m) _Pragma("unroll") for (int k = 0; k < 2; ++k) dst[m][k] = *(const LAS bf16x8*)(lds + PG8_SA(b, h) + aoff + m * 2048 + k * 1024); } while (0)
; #define PG8_LDB(dst, b, h) do { _Pragma("unroll") for (int n = 0; n < 2; ++n) _Pragma("unroll") for (int k = 0; k < 2; ++k) dst[n][k] = *(const LAS bf16x8*)(lds + PG8_SB(b, h) + boff + n * 2048 + k * 1024); } while (0)
; #define PG8_MMA(ai, bj, At, Bt) do { __builtin_amdgcn_s_setprio(1); _Pragma("unroll") for (int m = 0; m < 4; ++m) _Pragma("unroll") for (int n = 0; n < 2; ++n) _Pragma("unroll") for (int k = 0; k < 2; ++k) \
;         acc[ai][bj][m][n] = __builtin_amdgcn_mfma_f32_16x16x32_bf16(Bt[n][k], At[m][k], acc[ai][bj][m][n], 0, 0, 0); __builtin_amdgcn_s_setprio(0); } while (0)
; #define PG8_WAIT_V(n) asm volatile("s_waitcnt vmcnt(" #n ")" ::: "memory")
; #define PG8_WAIT_L(n) asm volatile("s_waitcnt lgkmcnt(" #n ")" ::: "memory")
; #define PG8_BAR __builtin_amdgcn_s_barrier()
; #define PG8_SCHED __builtin_amdgcn_sched_barrier(0)
; template <class Epi>
; __device__ __forceinline__ void gemm_phase(LAS unsigned char* lds, const int tid, const Gemm g, const StaticOrder& S, const Epi& E) {
;     ...
;             PG8_LDA(At, 0, 1); PG8_STAGE(PG8_SB(0, 0), b2, voffB); PG8_STAGE(PG8_SB(0, 1), b2 + hstepB, voffB); PG8_STAGE(PG8_SA(0, 0), a2, voffA);
;             PG8_WAIT_V(8); PG8_WAIT_L(0); PG8_BAR; PG8_MMA(1, 0, At, B0); PG8_MMA(1, 1, At, B1); PG8_BAR; PG8_SCHED;
;             PG8_LDB(B0, 1, 0); PG8_LDB(B1, 1, 1); PG8_SCHED; PG8_LDA(At, 1, 0); PG8_STAGE(PG8_SA(0, 1), a2 + hstepA, voffA);
;             PG8_WAIT_V(8); PG8_WAIT_L(0); PG8_BAR; PG8_MMA(0, 0, At, B0); PG8_MMA(0, 1, At, B1); PG8_BAR; PG8_SCHED;
	s_setprio 1
	v_mfma_f32_16x16x32_bf16 v[60:63], v[156:159], v[188:191], v[60:63]
	v_mfma_f32_16x16x32_bf16 v[52:55], v[164:167], v[188:191], v[52:55]
	v_mfma_f32_16x16x32_bf16 v[44:47], v[156:159], v[196:199], v[44:47]
	v_mfma_f32_16x16x32_bf16 v[36:39], v[164:167], v[196:199], v[36:39]
	v_mfma_f32_16x16x32_bf16 v[28:31], v[156:159], v[204:207], v[28:31]
	v_mfma_f32_16x16x32_bf16 v[20:23], v[164:167], v[204:207], v[20:23]
	v_mfma_f32_16x16x32_bf16 v[12:15], v[156:159], v[212:215], v[12:15]
	v_mfma_f32_16x16x32_bf16 v[4:7], v[164:167], v[212:215], v[4:7]
	v_mfma_f32_16x16x32_bf16 v[60:63], v[160:163], v[192:195], v[60:63]
	v_mfma_f32_16x16x32_bf16 v[52:55], v[168:171], v[192:195], v[52:55]
	v_mfma_f32_16x16x32_bf16 v[44:47], v[160:163], v[200:203], v[44:47]
	v_mfma_f32_16x16x32_bf16 v[36:39], v[168:171], v[200:203], v[36:39]
	v_mfma_f32_16x16x32_bf16 v[28:31], v[160:163], v[208:211], v[28:31]
	v_mfma_f32_16x16x32_bf16 v[20:23], v[168:171], v[208:211], v[20:23]
	v_mfma_f32_16x16x32_bf16 v[12:15], v[160:163], v[216:219], v[12:15]
	v_mfma_f32_16x16x32_bf16 v[4:7], v[168:171], v[216:219], v[4:7]
	v_mfma_f32_16x16x32_bf16 v[56:59], v[172:175], v[188:191], v[56:59]
	v_mfma_f32_16x16x32_bf16 v[48:51], v[180:183], v[188:191], v[48:51]
	v_mfma_f32_16x16x32_bf16 v[40:43], v[172:175], v[196:199], v[40:43]
	v_mfma_f32_16x16x32_bf16 v[32:35], v[180:183], v[196:199], v[32:35]
	v_mfma_f32_16x16x32_bf16 v[24:27], v[172:175], v[204:207], v[24:27]
	v_mfma_f32_16x16x32_bf16 v[16:19], v[180:183], v[204:207], v[16:19]
	v_mfma_f32_16x16x32_bf16 v[8:11], v[172:175], v[212:215], v[8:11]
	v_mfma_f32_16x16x32_bf16 v[0:3], v[180:183], v[212:215], v[0:3]
	v_mfma_f32_16x16x32_bf16 v[56:59], v[176:179], v[192:195], v[56:59]
	v_mfma_f32_16x16x32_bf16 v[48:51], v[184:187], v[192:195], v[48:51]
	v_mfma_f32_16x16x32_bf16 v[40:43], v[176:179], v[200:203], v[40:43]
	v_mfma_f32_16x16x32_bf16 v[32:35], v[184:187], v[200:203], v[32:35]
	v_mfma_f32_16x16x32_bf16 v[24:27], v[176:179], v[208:211], v[24:27]
	v_mfma_f32_16x16x32_bf16 v[16:19], v[184:187], v[208:211], v[16:19]
	v_mfma_f32_16x16x32_bf16 v[8:11], v[176:179], v[216:219], v[8:11]
	v_mfma_f32_16x16x32_bf16 v[0:3], v[184:187], v[216:219], v[0:3]
	s_setprio 0
	s_barrier
	v_lshl_add_u64 v[224:225], s[30:31], 0, v[134:135]
	s_mov_b32 m0, s41
	v_lshl_add_u64 v[226:227], s[30:31], 0, v[130:131]
	global_load_lds_dwordx4 v[224:225], off
	s_mov_b32 m0, s42
	s_nop 0
	global_load_lds_dwordx4 v[226:227], off
	s_add_i32 s59, 0, 0x18000
	s_add_i32 s60, 0, 0x1c000
	v_add_u32_e32 v168, s59, v151
	v_add_u32_e32 v184, s60, v151
	ds_read_b128 v[156:159], v168
	ds_read_b128 v[160:163], v168 offset:1024
	ds_read_b128 v[164:167], v168 offset:2048
	ds_read_b128 v[168:171], v168 offset:3072
	ds_read_b128 v[172:175], v184
	ds_read_b128 v[176:179], v184 offset:1024
	ds_read_b128 v[180:183], v184 offset:2048
	ds_read_b128 v[184:187], v184 offset:3072
	s_add_u32 s30, s30, 0x40000
	s_addc_u32 s31, s31, 0
	s_mov_b32 m0, s43
	v_lshl_add_u64 v[228:229], s[30:31], 0, v[134:135]
	ds_read_b128 v[188:191], v153 offset:32768
	ds_read_b128 v[192:195], v153 offset:33792
	ds_read_b128 v[196:199], v153 offset:34816
	ds_read_b128 v[200:203], v153 offset:35840
	ds_read_b128 v[204:207], v153 offset:36864
	ds_read_b128 v[208:211], v153 offset:37888
	ds_read_b128 v[212:215], v153 offset:38912
	ds_read_b128 v[216:219], v153 offset:39936
	global_load_lds_dwordx4 v[228:229], off
	v_lshl_add_u64 v[228:229], s[30:31], 0, v[130:131]
	s_mov_b32 m0, s44
	s_nop 0
	global_load_lds_dwordx4 v[228:229], off
	s_waitcnt vmcnt(8)
	s_waitcnt lgkmcnt(0)
	s_barrier
; #define PG8_STAGE(bufoff, gbase, voff) do { _Pragma("unroll") for (int _i = 0; _i < 2; ++_i) \
;         __builtin_amdgcn_global_load_lds((const unsigned*)((const char*)(gbase) + (voff)[_i]), (LAS unsigned*)(lds + (bufoff) + ldsw + _i * 8192), 16, 0, 0); } while (0)
; #define PG8_LDA(dst, b, h) do { _Pragma("unroll") for (int m = 0; m < 4; ++m) _Pragma("unroll") for (int k = 0; k < 2; ++k) dst[m][k] = *(const LAS bf16x8*)(lds + PG8_SA(b, h) + aoff + m * 2048 + k * 1024); } while (0)
; #define PG8_MMA(ai, bj, At, Bt) do { __builtin_amdgcn_s_setprio(1); _Pragma("unroll") for (int m = 0; m < 4; ++m) _Pragma("unroll") for (int n = 0; n < 2; ++n) _Pragma("unroll") for (int k = 0; k < 2; ++k) \
;         acc[ai][bj][m][n] = __builtin_amdgcn_mfma_f32_16x16x32_bf16(Bt[n][k], At[m][k], acc[ai][bj][m][n], 0, 0, 0); __builtin_amdgcn_s_setprio(0); } while (0)
; #define PG8_WAIT_V(n) asm volatile("s_waitcnt vmcnt(" #n ")" ::: "memory")
; #define PG8_WAIT_L(n) asm volatile("s_waitcnt lgkmcnt(" #n ")" ::: "memory")
; #define PG8_BAR __builtin_amdgcn_s_barrier()
; #define PG8_SCHED __builtin_amdgcn_sched_barrier(0)
; template <class Epi>
; __device__ __forceinline__ void gemm_phase(LAS unsigned char* lds, const int tid, const Gemm g, const StaticOrder& S, const Epi& E) {
;     ...
;             PG8_WAIT_V(8); PG8_WAIT_L(0); PG8_BAR; PG8_MMA(0, 0, At, B0); PG8_MMA(0, 1, At, B1); PG8_BAR; PG8_SCHED;
;             PG8_LDA(At, 1, 1); PG8_STAGE(PG8_SB(1, 0), b3, voffB); PG8_STAGE(PG8_SB(1, 1), b3 + hstepB, voffB); PG8_STAGE(PG8_SA(1, 0), a3, voffA);
;             PG8_WAIT_V(8); PG8_WAIT_L(0); PG8_BAR; PG8_MMA(1, 0, At, B0); PG8_MMA(1, 1, At, B1); PG8_BAR; PG8_SCHED;
	s_setprio 1
	v_mfma_f32_16x16x32_bf16 v[120:123], v[156:159], v[188:191], v[120:123]
	v_mfma_f32_16x16x32_bf16 v[116:119], v[164:167], v[188:191], v[116:119]
	v_mfma_f32_16x16x32_bf16 v[108:111], v[156:159], v[196:199], v[108:111]
	v_mfma_f32_16x16x32_bf16 v[100:103], v[164:167], v[196:199], v[100:103]
	v_mfma_f32_16x16x32_bf16 v[92:95], v[156:159], v[204:207], v[92:95]
	v_mfma_f32_16x16x32_bf16 v[84:87], v[164:167], v[204:207], v[84:87]
	v_mfma_f32_16x16x32_bf16 v[76:79], v[156:159], v[212:215], v[76:79]
	v_mfma_f32_16x16x32_bf16 v[68:71], v[164:167], v[212:215], v[68:71]
	v_mfma_f32_16x16x32_bf16 v[120:123], v[160:163], v[192:195], v[120:123]
	v_mfma_f32_16x16x32_bf16 v[116:119], v[168:171], v[192:195], v[116:119]
	v_mfma_f32_16x16x32_bf16 v[108:111], v[160:163], v[200:203], v[108:111]
	v_mfma_f32_16x16x32_bf16 v[100:103], v[168:171], v[200:203], v[100:103]
	v_mfma_f32_16x16x32_bf16 v[92:95], v[160:163], v[208:211], v[92:95]
	v_mfma_f32_16x16x32_bf16 v[84:87], v[168:171], v[208:211], v[84:87]
	v_mfma_f32_16x16x32_bf16 v[76:79], v[160:163], v[216:219], v[76:79]
	v_mfma_f32_16x16x32_bf16 v[68:71], v[168:171], v[216:219], v[68:71]
	v_mfma_f32_16x16x32_bf16 v[124:127], v[172:175], v[188:191], v[124:127]
	v_mfma_f32_16x16x32_bf16 v[112:115], v[180:183], v[188:191], v[112:115]
	v_mfma_f32_16x16x32_bf16 v[104:107], v[172:175], v[196:199], v[104:107]
	v_mfma_f32_16x16x32_bf16 v[96:99], v[180:183], v[196:199], v[96:99]
	v_mfma_f32_16x16x32_bf16 v[88:91], v[172:175], v[204:207], v[88:91]
	v_mfma_f32_16x16x32_bf16 v[80:83], v[180:183], v[204:207], v[80:83]
	v_mfma_f32_16x16x32_bf16 v[72:75], v[172:175], v[212:215], v[72:75]
	v_mfma_f32_16x16x32_bf16 v[64:67], v[180:183], v[212:215], v[64:67]
	v_mfma_f32_16x16x32_bf16 v[124:127], v[176:179], v[192:195], v[124:127]
	v_mfma_f32_16x16x32_bf16 v[112:115], v[184:187], v[192:195], v[112:115]
	v_mfma_f32_16x16x32_bf16 v[104:107], v[176:179], v[200:203], v[104:107]
	v_mfma_f32_16x16x32_bf16 v[96:99], v[184:187], v[200:203], v[96:99]
	v_mfma_f32_16x16x32_bf16 v[88:91], v[176:179], v[208:211], v[88:91]
	v_mfma_f32_16x16x32_bf16 v[80:83], v[184:187], v[208:211], v[80:83]
	v_mfma_f32_16x16x32_bf16 v[72:75], v[176:179], v[216:219], v[72:75]
	v_mfma_f32_16x16x32_bf16 v[64:67], v[184:187], v[216:219], v[64:67]
	s_setprio 0
	s_barrier
	s_add_i32 s30, s59, s38
	v_lshl_add_u64 v[220:221], v[220:221], 0, s[12:13]
	s_mov_b32 m0, s30
	ds_read_b128 v[188:191], v153 offset:49152
	ds_read_b128 v[192:195], v153 offset:50176
	ds_read_b128 v[196:199], v153 offset:51200
	ds_read_b128 v[200:203], v153 offset:52224
	ds_read_b128 v[204:207], v153 offset:53248
	ds_read_b128 v[208:211], v153 offset:54272
	ds_read_b128 v[212:215], v153 offset:55296
	ds_read_b128 v[216:219], v153 offset:56320
	global_load_lds_dwordx4 v[220:221], off
	s_add_i32 m0, s30, 0x2000
	s_add_u32 s28, s28, 0x40080
	v_lshl_add_u64 v[220:221], v[222:223], 0, s[12:13]
	s_addc_u32 s29, s29, 0
	s_add_i32 s30, s60, s38
	global_load_lds_dwordx4 v[220:221], off
	v_lshl_add_u64 v[220:221], s[28:29], 0, v[132:133]
	s_mov_b32 m0, s30
	s_nop 0
	global_load_lds_dwordx4 v[220:221], off
	v_lshl_add_u64 v[220:221], s[28:29], 0, v[128:129]
	s_add_i32 m0, s30, 0x2000
	s_nop 0
	global_load_lds_dwordx4 v[220:221], off
	s_waitcnt vmcnt(6)
	s_waitcnt lgkmcnt(0)
	s_barrier
	s_setprio 1
	v_mfma_f32_16x16x32_bf16 v[60:63], v[156:159], v[188:191], v[60:63]
	v_mfma_f32_16x16x32_bf16 v[52:55], v[164:167], v[188:191], v[52:55]
	v_mfma_f32_16x16x32_bf16 v[44:47], v[156:159], v[196:199], v[44:47]
	v_mfma_f32_16x16x32_bf16 v[36:39], v[164:167], v[196:199], v[36:39]
	v_mfma_f32_16x16x32_bf16 v[28:31], v[156:159], v[204:207], v[28:31]
	v_mfma_f32_16x16x32_bf16 v[20:23], v[164:167], v[204:207], v[20:23]
	v_mfma_f32_16x16x32_bf16 v[12:15], v[156:159], v[212:215], v[12:15]
	v_mfma_f32_16x16x32_bf16 v[4:7], v[164:167], v[212:215], v[4:7]
	v_mfma_f32_16x16x32_bf16 v[60:63], v[160:163], v[192:195], v[60:63]
	v_mfma_f32_16x16x32_bf16 v[52:55], v[168:171], v[192:195], v[52:55]
	v_mfma_f32_16x16x32_bf16 v[44:47], v[160:163], v[200:203], v[44:47]
	v_mfma_f32_16x16x32_bf16 v[36:39], v[168:171], v[200:203], v[36:39]
	v_mfma_f32_16x16x32_bf16 v[28:31], v[160:163], v[208:211], v[28:31]
	v_mfma_f32_16x16x32_bf16 v[20:23], v[168:171], v[208:211], v[20:23]
	v_mfma_f32_16x16x32_bf16 v[12:15], v[160:163], v[216:219], v[12:15]
	v_mfma_f32_16x16x32_bf16 v[4:7], v[168:171], v[216:219], v[4:7]
	v_mfma_f32_16x16x32_bf16 v[56:59], v[172:175], v[188:191], v[56:59]
	v_mfma_f32_16x16x32_bf16 v[48:51], v[180:183], v[188:191], v[48:51]
	v_mfma_f32_16x16x32_bf16 v[40:43], v[172:175], v[196:199], v[40:43]
	v_mfma_f32_16x16x32_bf16 v[32:35], v[180:183], v[196:199], v[32:35]
	v_mfma_f32_16x16x32_bf16 v[24:27], v[172:175], v[204:207], v[24:27]
	v_mfma_f32_16x16x32_bf16 v[16:19], v[180:183], v[204:207], v[16:19]
	v_mfma_f32_16x16x32_bf16 v[8:11], v[172:175], v[212:215], v[8:11]
	v_mfma_f32_16x16x32_bf16 v[0:3], v[180:183], v[212:215], v[0:3]
	v_mfma_f32_16x16x32_bf16 v[56:59], v[176:179], v[192:195], v[56:59]
	v_mfma_f32_16x16x32_bf16 v[48:51], v[184:187], v[192:195], v[48:51]
	v_mfma_f32_16x16x32_bf16 v[40:43], v[176:179], v[200:203], v[40:43]
	v_mfma_f32_16x16x32_bf16 v[32:35], v[184:187], v[200:203], v[32:35]
	v_mfma_f32_16x16x32_bf16 v[24:27], v[176:179], v[208:211], v[24:27]
	v_mfma_f32_16x16x32_bf16 v[16:19], v[184:187], v[208:211], v[16:19]
	v_mfma_f32_16x16x32_bf16 v[8:11], v[176:179], v[216:219], v[8:11]
	v_mfma_f32_16x16x32_bf16 v[0:3], v[184:187], v[216:219], v[0:3]
	s_setprio 0
	s_barrier
	s_add_u32 s25, s25, 0x100
	s_addc_u32 s57, s57, 0
	s_add_u32 s26, s26, 0x100
	s_addc_u32 s27, s27, 0
	s_cmp_ge_i32 s58, s46
	s_cbranch_scc1 .LBB0_266
